# rope epilogue of ret-in: cos/sin loads prefetched 4 rounds deep into free registers instead of 8 serialized load-wait rounds (on top of norm-loop consolidation)
# baseline (speedup 1.0000x reference)
;     __device__ __forceinline__ void operator()(const f32x4 (&acc)[2][2][4][2], const Unit& u, int wr, int wc, int fr, int fq) const {
;         const int row0 = u.pm * BM + wr * 64 + fr, cl = wc * 32 + 8 * fq;
;         if (u.pn < 16) {
;             const bool isk = u.pn >= 8; const int head = u.pn & 7; bf16_t* base = isk ? Kb : Q;
;             const float l2g = log1pf(-exp2f(-5.0f - (float)head)) * 1.4426950408889634f;
; #pragma unroll
;             for (int ai = 0; ai < 2; ++ai)
; #pragma unroll
;                 for (int m = 0; m < 4; ++m) { const int row = row0 + ai * HALF + m * 16;
;                     const float tcp = (float)((row & 63) + 1);
;                     const float sc = isk ? 0.0625f * exp2f(-tcp * l2g) : exp2f(tcp * l2g);
;                     const f32x4 c0 = *(const f32x4*)(cosT + (size_t)row * 128 + cl), c1 = *(const f32x4*)(cosT + (size_t)row * 128 + cl + 4);
;                     const f32x4 s0 = *(const f32x4*)(sinT + (size_t)row * 128 + cl), s1 = *(const f32x4*)(sinT + (size_t)row * 128 + cl + 4);
.LBB0_301:
	v_lshlrev_b32_e32 v250, 9, v150
	v_lshl_add_u32 v250, v152, 2, v250
	global_load_dwordx4 v[190:193], v250, s[14:15] offset:16
	global_load_dwordx4 v[186:189], v250, s[14:15]
	global_load_dwordx4 v[198:201], v250, s[16:17] offset:16
	global_load_dwordx4 v[194:197], v250, s[16:17]
	v_add_u32_e32 v251, 0x2000, v250
	global_load_dwordx4 v[206:209], v251, s[14:15] offset:16
	global_load_dwordx4 v[202:205], v251, s[14:15]
	global_load_dwordx4 v[214:217], v251, s[16:17] offset:16
	global_load_dwordx4 v[210:213], v251, s[16:17]
	v_add_u32_e32 v251, 0x4000, v250
	global_load_dwordx4 v[222:225], v251, s[14:15] offset:16
	global_load_dwordx4 v[218:221], v251, s[14:15]
	global_load_dwordx4 v[230:233], v251, s[16:17] offset:16
	global_load_dwordx4 v[226:229], v251, s[16:17]
	v_add_u32_e32 v251, 0x6000, v250
	global_load_dwordx4 v[238:241], v251, s[14:15] offset:16
	global_load_dwordx4 v[234:237], v251, s[14:15]
	global_load_dwordx4 v[246:249], v251, s[16:17] offset:16
	global_load_dwordx4 v[242:245], v251, s[16:17]
	s_cmp_gt_i32 s12, 7
	s_cselect_b64 s[82:83], -1, 0
	s_cmp_lt_i32 s12, 8
	s_cselect_b64 s[80:81], -1, 0
	s_and_b32 s3, s12, 7
	v_cvt_f32_ubyte0_e32 v1, s3
	v_sub_f32_e32 v1, 0xc0a00000, v1
	v_cmp_gt_f32_e32 vcc, s52, v1
	s_and_b64 s[10:11], vcc, exec
	s_cselect_b32 s0, 0xffffffc0, 0
	v_cndmask_b32_e32 v130, 0, v162, vcc
	v_add_f32_e32 v1, v1, v130
	v_exp_f32_e32 v1, v1
	s_mov_b64 s[12:13], -1
	v_ldexp_f32 v1, v1, s0
	v_sub_f32_e32 v132, 1.0, v1
	v_add_f32_e32 v130, -1.0, v132
	v_sub_f32_e32 v131, v130, v132
	v_add_f32_e32 v131, 1.0, v131
	v_sub_f32_e64 v130, -v1, v130
	v_add_f32_e32 v133, v130, v131
	v_frexp_mant_f32_e32 v130, v132
	s_mov_b32 s0, 0x3f2aaaab
	v_cmp_gt_f32_e32 vcc, s0, v130
	v_cvt_f64_f32_e32 v[130:131], v132
	v_frexp_exp_i32_f64_e32 v130, v[130:131]
	v_subbrev_co_u32_e32 v130, vcc, 0, v130, vcc
	v_sub_u32_e32 v131, 0, v130
	v_ldexp_f32 v132, v132, v131
	v_ldexp_f32 v131, v133, v131
	v_add_f32_e32 v133, -1.0, v132
	v_add_f32_e32 v134, 1.0, v133
	v_sub_f32_e32 v134, v132, v134
	v_add_f32_e32 v134, v131, v134
	v_add_f32_e32 v135, v133, v134
	v_sub_f32_e32 v133, v135, v133
	v_sub_f32_e32 v133, v134, v133
	v_add_f32_e32 v134, 1.0, v132
	v_add_f32_e32 v136, -1.0, v134
	v_sub_f32_e32 v132, v132, v136
	v_add_f32_e32 v131, v131, v132
	v_add_f32_e32 v132, v134, v131
	v_sub_f32_e32 v134, v132, v134
	v_sub_f32_e32 v131, v131, v134
	v_rcp_f32_e32 v134, v132
	v_cvt_f32_i32_e32 v130, v130
	s_mov_b32 s0, 0x3f317218
	v_cmp_nlt_f32_e32 vcc, 1.0, v1
	v_mul_f32_e32 v136, v135, v134
	v_mul_f32_e32 v137, v132, v136
	v_fma_f32 v138, v136, v132, -v137
	v_fmac_f32_e32 v138, v136, v131
	v_add_f32_e32 v139, v137, v138
	v_sub_f32_e32 v151, v135, v139
	v_sub_f32_e32 v135, v135, v151
	v_sub_f32_e32 v137, v139, v137
	v_sub_f32_e32 v135, v135, v139
	v_add_f32_e32 v133, v133, v135
	v_sub_f32_e32 v135, v137, v138
	v_add_f32_e32 v133, v135, v133
	v_add_f32_e32 v135, v151, v133
	v_mul_f32_e32 v137, v134, v135
	v_mul_f32_e32 v138, v132, v137
	v_fma_f32 v132, v137, v132, -v138
	v_fmac_f32_e32 v132, v137, v131
	v_sub_f32_e32 v131, v151, v135
	v_add_f32_e32 v131, v133, v131
	v_add_f32_e32 v133, v138, v132
	v_sub_f32_e32 v139, v135, v133
	v_sub_f32_e32 v135, v135, v139
	v_sub_f32_e32 v138, v133, v138
	v_sub_f32_e32 v133, v135, v133
	v_add_f32_e32 v131, v131, v133
	v_sub_f32_e32 v132, v138, v132
	v_add_f32_e32 v131, v132, v131
	v_add_f32_e32 v132, v136, v137
	v_add_f32_e32 v131, v139, v131
	v_sub_f32_e32 v133, v132, v136
	v_mul_f32_e32 v131, v134, v131
	v_sub_f32_e32 v133, v137, v133
	v_add_f32_e32 v131, v133, v131
	v_mul_f32_e32 v136, 0x3f317218, v130
	v_add_f32_e32 v133, v132, v131
	v_fma_f32 v137, v130, s0, -v136
	v_mul_f32_e32 v134, v133, v133
	v_fmac_f32_e32 v137, 0xb102e308, v130
	v_sub_f32_e32 v130, v133, v132
	v_fmamk_f32 v135, v134, 0x3e9b6dac, v161
	v_sub_f32_e32 v130, v131, v130
	v_add_f32_e32 v131, v136, v137
	v_fmaak_f32 v135, v134, v135, 0x3f2aaada
	v_sub_f32_e32 v132, v131, v136
	v_ldexp_f32 v136, v133, 1
	v_mul_f32_e32 v133, v133, v134
	v_mul_f32_e32 v133, v133, v135
	v_add_f32_e32 v134, v136, v133
	v_sub_f32_e32 v135, v134, v136
	v_ldexp_f32 v130, v130, 1
	v_sub_f32_e32 v133, v133, v135
	v_add_f32_e32 v130, v130, v133
	v_add_f32_e32 v133, v134, v130
	v_sub_f32_e32 v134, v133, v134
	v_sub_f32_e32 v130, v130, v134
	v_add_f32_e32 v134, v131, v133
	v_sub_f32_e32 v135, v134, v131
	v_sub_f32_e32 v136, v134, v135
	v_sub_f32_e32 v132, v137, v132
	v_sub_f32_e32 v131, v131, v136
	v_sub_f32_e32 v133, v133, v135
	v_add_f32_e32 v131, v133, v131
	v_add_f32_e32 v133, v132, v130
	v_sub_f32_e32 v135, v133, v132
	v_sub_f32_e32 v136, v133, v135
	v_sub_f32_e32 v132, v132, v136
	v_sub_f32_e32 v130, v130, v135
	v_add_f32_e32 v131, v133, v131
	v_add_f32_e32 v130, v130, v132
	v_add_f32_e32 v132, v134, v131
	v_sub_f32_e32 v133, v132, v134
	v_sub_f32_e32 v131, v131, v133
	v_add_f32_e32 v130, v130, v131
	v_add_f32_e32 v130, v132, v130
	v_cndmask_b32_e32 v130, v163, v130, vcc
	v_cmp_neq_f32_e32 vcc, 1.0, v1
	s_mov_b32 s0, 0x33800000
	s_nop 0
	v_cndmask_b32_e32 v130, v164, v130, vcc
	v_cmp_gt_f32_e32 vcc, s0, v1
	s_nop 1
	v_cndmask_b32_e64 v1, v130, -v1, vcc
	v_add_u32_e32 v130, 1, v166
	v_mul_f32_e32 v1, 0x3fb8aa3b, v1
	v_cvt_f32_ubyte0_e32 v135, v130
	v_mul_f32_e32 v136, v1, v135
	s_and_b64 vcc, exec, s[80:81]
	v_cmp_gt_f32_e64 s[10:11], s52, v136
	s_cbranch_vccz .LBB0_303
	s_nop 0
	v_cndmask_b32_e64 v130, 0, v162, s[10:11]
	v_fmac_f32_e32 v130, v1, v135
	v_exp_f32_e32 v130, v130
	v_cndmask_b32_e64 v131, 0, v165, s[10:11]
	s_mov_b64 s[12:13], 0
	v_ldexp_f32 v134, v130, v131

; __device__ __forceinline__ u32x4 pack8(const f32x4& a, const f32x4& b) { u32x4 w; w.x = cvt_pk_bf16(a[0], a[1]); w.y = cvt_pk_bf16(a[2], a[3]); w.z = cvt_pk_bf16(b[0], b[1]); w.w = cvt_pk_bf16(b[2], b[3]); return w; }
;     __device__ __forceinline__ void operator()(const f32x4 (&acc)[2][2][4][2], const Unit& u, int wr, int wc, int fr, int fq) const {
;     ...
;                 for (int m = 0; m < 4; ++m) { const int row = row0 + ai * HALF + m * 16;
;                     const float tcp = (float)((row & 63) + 1);
;                     const float sc = isk ? 0.0625f * exp2f(-tcp * l2g) : exp2f(tcp * l2g);
;                     const f32x4 c0 = *(const f32x4*)(cosT + (size_t)row * 128 + cl), c1 = *(const f32x4*)(cosT + (size_t)row * 128 + cl + 4);
;                     const f32x4 s0 = *(const f32x4*)(sinT + (size_t)row * 128 + cl), s1 = *(const f32x4*)(sinT + (size_t)row * 128 + cl + 4);
;                     const f32x4 a0 = acc[ai][0][m][0], a1 = acc[ai][0][m][1], b0 = acc[ai][1][m][0], b1 = acc[ai][1][m][1];
;                     const f32x4 o10 = (a0 * c0 - b0 * s0) * sc, o11 = (a1 * c1 - b1 * s1) * sc, o20 = (b0 * c0 + a0 * s0) * sc, o21 = (b1 * c1 + a1 * s1) * sc;
;                     bf16_t* rowp = base + (size_t)row * 2048 + head * 256 + cl;
;                     *(u32x4*)rowp = pack8(o10, o11); *(u32x4*)(rowp + HALF) = pack8(o20, o21); }
.LBB0_305:
	s_and_b64 s[10:11], s[82:83], exec
	s_mov_b32 s0, 0x25f00000
	s_cselect_b32 s0, s0, 0x21f00000
	s_add_u32 s0, s48, s0
	v_ashrrev_i32_e32 v151, 31, v150
	s_addc_u32 s1, s49, 0
	v_ashrrev_i32_e32 v153, 31, v152
	s_lshl_b32 s3, s3, 9
	v_lshlrev_b64 v[138:139], 9, v[150:151]
	s_add_u32 s10, s0, s3
	v_lshl_add_u64 v[154:155], s[14:15], 0, v[138:139]
	v_lshlrev_b64 v[132:133], 2, v[152:153]
	v_lshl_add_u64 v[138:139], s[16:17], 0, v[138:139]
	s_addc_u32 s11, s1, 0
	v_lshl_add_u64 v[168:169], v[154:155], 0, v[132:133]
	v_lshl_add_u64 v[138:139], v[138:139], 0, v[132:133]
	v_lshl_add_u64 v[130:131], v[152:153], 1, s[10:11]
	s_mov_b64 s[82:83], -1
	s_andn2_b64 vcc, exec, s[80:81]
	s_waitcnt vmcnt(12)
	v_mov_b64_e32 v[152:153], v[190:191]
	v_mov_b64_e32 v[154:155], v[192:193]
	v_mov_b64_e32 v[168:169], v[186:187]
	v_mov_b64_e32 v[170:171], v[188:189]
	v_mov_b64_e32 v[172:173], v[198:199]
	v_mov_b64_e32 v[174:175], v[200:201]
	v_mov_b64_e32 v[176:177], v[194:195]
	v_mov_b64_e32 v[178:179], v[196:197]
	v_add_u32_e32 v251, 0x10000, v250
	global_load_dwordx4 v[190:193], v251, s[14:15] offset:16
	global_load_dwordx4 v[186:189], v251, s[14:15]
	global_load_dwordx4 v[198:201], v251, s[16:17] offset:16
	global_load_dwordx4 v[194:197], v251, s[16:17]
	v_pk_mul_f32 v[184:185], v[122:123], v[172:173]
	v_pk_mul_f32 v[182:183], v[124:125], v[174:175]
	v_pk_fma_f32 v[184:185], v[114:115], v[152:153], v[184:185] neg_lo:[0,0,1] neg_hi:[0,0,1]
	v_pk_mul_f32 v[114:115], v[114:115], v[172:173]
	v_pk_mul_f32 v[180:181], v[126:127], v[176:177]
	v_pk_fma_f32 v[182:183], v[116:117], v[154:155], v[182:183] neg_lo:[0,0,1] neg_hi:[0,0,1]
	v_pk_mul_f32 v[116:117], v[116:117], v[174:175]
	v_pk_fma_f32 v[114:115], v[122:123], v[152:153], v[114:115]
	v_pk_mul_f32 v[138:139], v[128:129], v[178:179]
	v_pk_fma_f32 v[180:181], v[118:119], v[168:169], v[180:181] neg_lo:[0,0,1] neg_hi:[0,0,1]
	v_pk_mul_f32 v[118:119], v[118:119], v[176:177]
	v_pk_fma_f32 v[116:117], v[124:125], v[154:155], v[116:117]
	v_pk_mul_f32 v[124:125], v[134:135], v[114:115] op_sel_hi:[0,1]
	v_lshlrev_b64 v[114:115], 12, v[150:151]
	v_pk_fma_f32 v[138:139], v[120:121], v[170:171], v[138:139] neg_lo:[0,0,1] neg_hi:[0,0,1]
	v_pk_mul_f32 v[180:181], v[134:135], v[180:181] op_sel_hi:[0,1]
	v_pk_mul_f32 v[120:121], v[120:121], v[178:179]
	v_pk_fma_f32 v[118:119], v[126:127], v[168:169], v[118:119]
	v_lshl_add_u64 v[126:127], v[130:131], 0, v[114:115]
	v_cvt_pk_bf16_f32 v114, v180, v181
	v_pk_mul_f32 v[138:139], v[134:135], v[138:139] op_sel_hi:[0,1]
	v_pk_mul_f32 v[182:183], v[134:135], v[182:183] op_sel_hi:[0,1]
	v_pk_mul_f32 v[184:185], v[134:135], v[184:185] op_sel_hi:[0,1]
	v_pk_fma_f32 v[120:121], v[128:129], v[170:171], v[120:121]
	v_pk_mul_f32 v[118:119], v[134:135], v[118:119] op_sel_hi:[0,1]
	v_pk_mul_f32 v[122:123], v[134:135], v[116:117] op_sel_hi:[0,1]
	v_cvt_pk_bf16_f32 v115, v138, v139
	v_cvt_pk_bf16_f32 v116, v184, v185
	v_cvt_pk_bf16_f32 v117, v182, v183
	global_store_dwordx4 v[126:127], v[114:117], off
	v_pk_mul_f32 v[120:121], v[134:135], v[120:121] op_sel_hi:[0,1]
	s_nop 0
	v_cvt_pk_bf16_f32 v114, v118, v119
	v_cvt_pk_bf16_f32 v115, v120, v121
	v_cvt_pk_bf16_f32 v116, v124, v125
	v_cvt_pk_bf16_f32 v117, v122, v123
	global_store_dwordx4 v[126:127], v[114:117], off offset:256
	s_nop 1
	v_add_u32_e32 v114, 17, v166
	v_cvt_f32_ubyte0_e32 v115, v114
	v_cndmask_b32_e64 v114, 0, 1, s[80:81]
	v_mul_f32_e32 v116, v1, v115
	v_cmp_ne_u32_e64 s[10:11], 1, v114
	v_cmp_gt_f32_e64 s[12:13], s52, v116
	s_cbranch_vccnz .LBB0_307
	s_nop 0
	v_cndmask_b32_e64 v114, 0, v162, s[12:13]
	v_fmac_f32_e32 v114, v1, v115
	v_exp_f32_e32 v114, v114
	v_cndmask_b32_e64 v117, 0, v165, s[12:13]
	s_mov_b64 s[82:83], 0
	v_ldexp_f32 v114, v114, v117

; __device__ __forceinline__ u32x4 pack8(const f32x4& a, const f32x4& b) { u32x4 w; w.x = cvt_pk_bf16(a[0], a[1]); w.y = cvt_pk_bf16(a[2], a[3]); w.z = cvt_pk_bf16(b[0], b[1]); w.w = cvt_pk_bf16(b[2], b[3]); return w; }
;     __device__ __forceinline__ void operator()(const f32x4 (&acc)[2][2][4][2], const Unit& u, int wr, int wc, int fr, int fq) const {
;     ...
;                 for (int m = 0; m < 4; ++m) { const int row = row0 + ai * HALF + m * 16;
;                     const float tcp = (float)((row & 63) + 1);
;                     const float sc = isk ? 0.0625f * exp2f(-tcp * l2g) : exp2f(tcp * l2g);
;                     const f32x4 c0 = *(const f32x4*)(cosT + (size_t)row * 128 + cl), c1 = *(const f32x4*)(cosT + (size_t)row * 128 + cl + 4);
;                     const f32x4 s0 = *(const f32x4*)(sinT + (size_t)row * 128 + cl), s1 = *(const f32x4*)(sinT + (size_t)row * 128 + cl + 4);
;                     const f32x4 a0 = acc[ai][0][m][0], a1 = acc[ai][0][m][1], b0 = acc[ai][1][m][0], b1 = acc[ai][1][m][1];
;                     const f32x4 o10 = (a0 * c0 - b0 * s0) * sc, o11 = (a1 * c1 - b1 * s1) * sc, o20 = (b0 * c0 + a0 * s0) * sc, o21 = (b1 * c1 + a1 * s1) * sc;
;                     bf16_t* rowp = base + (size_t)row * 2048 + head * 256 + cl;
;                     *(u32x4*)rowp = pack8(o10, o11); *(u32x4*)(rowp + HALF) = pack8(o20, o21); }
.LBB0_309:
	v_or_b32_e32 v138, 16, v150
	v_ashrrev_i32_e32 v139, 31, v138
	v_lshlrev_b64 v[126:127], 9, v[138:139]
	v_lshl_add_u64 v[118:119], s[14:15], 0, v[126:127]
	v_lshl_add_u64 v[126:127], s[16:17], 0, v[126:127]
	v_lshl_add_u64 v[122:123], v[118:119], 0, v[132:133]
	v_lshl_add_u64 v[152:153], v[126:127], 0, v[132:133]
	s_mov_b64 s[80:81], -1
	s_and_b64 vcc, exec, s[10:11]
	s_waitcnt vmcnt(14)
	v_mov_b64_e32 v[118:119], v[206:207]
	v_mov_b64_e32 v[120:121], v[208:209]
	v_mov_b64_e32 v[122:123], v[202:203]
	v_mov_b64_e32 v[124:125], v[204:205]
	v_mov_b64_e32 v[126:127], v[214:215]
	v_mov_b64_e32 v[128:129], v[216:217]
	v_mov_b64_e32 v[152:153], v[210:211]
	v_mov_b64_e32 v[154:155], v[212:213]
	v_add_u32_e32 v251, 0x12000, v250
	global_load_dwordx4 v[206:209], v251, s[14:15] offset:16
	global_load_dwordx4 v[202:205], v251, s[14:15]
	global_load_dwordx4 v[214:217], v251, s[16:17] offset:16
	global_load_dwordx4 v[210:213], v251, s[16:17]
	v_pk_mul_f32 v[174:175], v[106:107], v[126:127]
	v_pk_mul_f32 v[172:173], v[108:109], v[128:129]
	v_pk_fma_f32 v[174:175], v[98:99], v[118:119], v[174:175] neg_lo:[0,0,1] neg_hi:[0,0,1]
	v_pk_mul_f32 v[98:99], v[98:99], v[126:127]
	v_pk_mul_f32 v[170:171], v[110:111], v[152:153]
	v_pk_fma_f32 v[172:173], v[100:101], v[120:121], v[172:173] neg_lo:[0,0,1] neg_hi:[0,0,1]
	v_pk_mul_f32 v[100:101], v[100:101], v[128:129]
	v_pk_fma_f32 v[98:99], v[106:107], v[118:119], v[98:99]
	v_pk_mul_f32 v[168:169], v[112:113], v[154:155]
	v_pk_fma_f32 v[170:171], v[102:103], v[122:123], v[170:171] neg_lo:[0,0,1] neg_hi:[0,0,1]
	v_pk_mul_f32 v[102:103], v[102:103], v[152:153]
	v_pk_fma_f32 v[100:101], v[108:109], v[120:121], v[100:101]
	v_pk_mul_f32 v[108:109], v[114:115], v[98:99] op_sel_hi:[0,1]
	v_lshlrev_b64 v[98:99], 12, v[138:139]
	v_pk_fma_f32 v[168:169], v[104:105], v[124:125], v[168:169] neg_lo:[0,0,1] neg_hi:[0,0,1]
	v_pk_mul_f32 v[170:171], v[114:115], v[170:171] op_sel_hi:[0,1]
	v_pk_mul_f32 v[104:105], v[104:105], v[154:155]
	v_pk_fma_f32 v[102:103], v[110:111], v[122:123], v[102:103]
	v_lshl_add_u64 v[110:111], v[130:131], 0, v[98:99]
	v_cvt_pk_bf16_f32 v98, v170, v171
	v_pk_mul_f32 v[168:169], v[114:115], v[168:169] op_sel_hi:[0,1]
	v_pk_mul_f32 v[172:173], v[114:115], v[172:173] op_sel_hi:[0,1]
	v_pk_mul_f32 v[174:175], v[114:115], v[174:175] op_sel_hi:[0,1]
	v_pk_fma_f32 v[104:105], v[112:113], v[124:125], v[104:105]
	v_pk_mul_f32 v[102:103], v[114:115], v[102:103] op_sel_hi:[0,1]
	v_pk_mul_f32 v[106:107], v[114:115], v[100:101] op_sel_hi:[0,1]
	v_cvt_pk_bf16_f32 v99, v168, v169
	v_cvt_pk_bf16_f32 v100, v174, v175
	v_cvt_pk_bf16_f32 v101, v172, v173
	global_store_dwordx4 v[110:111], v[98:101], off
	v_pk_mul_f32 v[104:105], v[114:115], v[104:105] op_sel_hi:[0,1]
	s_nop 0
	v_cvt_pk_bf16_f32 v98, v102, v103
	v_cvt_pk_bf16_f32 v99, v104, v105
	v_cvt_pk_bf16_f32 v100, v108, v109
	v_cvt_pk_bf16_f32 v101, v106, v107
	global_store_dwordx4 v[110:111], v[98:101], off offset:256
	s_nop 1
	v_add_u32_e32 v98, 33, v166
	v_cvt_f32_ubyte0_e32 v99, v98
	v_mul_f32_e32 v100, v1, v99
	v_cmp_gt_f32_e64 s[12:13], s52, v100
	s_cbranch_vccnz .LBB0_311
	s_nop 0
	v_cndmask_b32_e64 v98, 0, v162, s[12:13]
	v_fmac_f32_e32 v98, v1, v99
	v_exp_f32_e32 v98, v98
	v_cndmask_b32_e64 v101, 0, v165, s[12:13]
	s_mov_b64 s[80:81], 0
	v_ldexp_f32 v98, v98, v101

; __device__ __forceinline__ u32x4 pack8(const f32x4& a, const f32x4& b) { u32x4 w; w.x = cvt_pk_bf16(a[0], a[1]); w.y = cvt_pk_bf16(a[2], a[3]); w.z = cvt_pk_bf16(b[0], b[1]); w.w = cvt_pk_bf16(b[2], b[3]); return w; }
;     __device__ __forceinline__ void operator()(const f32x4 (&acc)[2][2][4][2], const Unit& u, int wr, int wc, int fr, int fq) const {
;     ...
;                 for (int m = 0; m < 4; ++m) { const int row = row0 + ai * HALF + m * 16;
;                     const float tcp = (float)((row & 63) + 1);
;                     const float sc = isk ? 0.0625f * exp2f(-tcp * l2g) : exp2f(tcp * l2g);
;                     const f32x4 c0 = *(const f32x4*)(cosT + (size_t)row * 128 + cl), c1 = *(const f32x4*)(cosT + (size_t)row * 128 + cl + 4);
;                     const f32x4 s0 = *(const f32x4*)(sinT + (size_t)row * 128 + cl), s1 = *(const f32x4*)(sinT + (size_t)row * 128 + cl + 4);
;                     const f32x4 a0 = acc[ai][0][m][0], a1 = acc[ai][0][m][1], b0 = acc[ai][1][m][0], b1 = acc[ai][1][m][1];
;                     const f32x4 o10 = (a0 * c0 - b0 * s0) * sc, o11 = (a1 * c1 - b1 * s1) * sc, o20 = (b0 * c0 + a0 * s0) * sc, o21 = (b1 * c1 + a1 * s1) * sc;
;                     bf16_t* rowp = base + (size_t)row * 2048 + head * 256 + cl;
;                     *(u32x4*)rowp = pack8(o10, o11); *(u32x4*)(rowp + HALF) = pack8(o20, o21); }
.LBB0_313:
	v_or_b32_e32 v122, 32, v150
	v_ashrrev_i32_e32 v123, 31, v122
	v_lshlrev_b64 v[110:111], 9, v[122:123]
	v_lshl_add_u64 v[102:103], s[14:15], 0, v[110:111]
	v_lshl_add_u64 v[110:111], s[16:17], 0, v[110:111]
	v_lshl_add_u64 v[106:107], v[102:103], 0, v[132:133]
	v_lshl_add_u64 v[118:119], v[110:111], 0, v[132:133]
	s_mov_b64 s[80:81], -1
	s_and_b64 vcc, exec, s[10:11]
	s_waitcnt vmcnt(16)
	v_mov_b64_e32 v[102:103], v[222:223]
	v_mov_b64_e32 v[104:105], v[224:225]
	v_mov_b64_e32 v[106:107], v[218:219]
	v_mov_b64_e32 v[108:109], v[220:221]
	v_mov_b64_e32 v[110:111], v[230:231]
	v_mov_b64_e32 v[112:113], v[232:233]
	v_mov_b64_e32 v[118:119], v[226:227]
	v_mov_b64_e32 v[120:121], v[228:229]
	v_add_u32_e32 v251, 0x14000, v250
	global_load_dwordx4 v[222:225], v251, s[14:15] offset:16
	global_load_dwordx4 v[218:221], v251, s[14:15]
	global_load_dwordx4 v[230:233], v251, s[16:17] offset:16
	global_load_dwordx4 v[226:229], v251, s[16:17]
	v_pk_mul_f32 v[138:139], v[90:91], v[110:111]
	v_pk_mul_f32 v[128:129], v[92:93], v[112:113]
	v_pk_fma_f32 v[138:139], v[82:83], v[102:103], v[138:139] neg_lo:[0,0,1] neg_hi:[0,0,1]
	v_pk_mul_f32 v[82:83], v[82:83], v[110:111]
	v_pk_mul_f32 v[126:127], v[94:95], v[118:119]
	v_pk_fma_f32 v[128:129], v[84:85], v[104:105], v[128:129] neg_lo:[0,0,1] neg_hi:[0,0,1]
	v_pk_mul_f32 v[84:85], v[84:85], v[112:113]
	v_pk_fma_f32 v[82:83], v[90:91], v[102:103], v[82:83]
	v_pk_mul_f32 v[124:125], v[96:97], v[120:121]
	v_pk_fma_f32 v[126:127], v[86:87], v[106:107], v[126:127] neg_lo:[0,0,1] neg_hi:[0,0,1]
	v_pk_mul_f32 v[86:87], v[86:87], v[118:119]
	v_pk_fma_f32 v[84:85], v[92:93], v[104:105], v[84:85]
	v_pk_mul_f32 v[92:93], v[98:99], v[82:83] op_sel_hi:[0,1]
	v_lshlrev_b64 v[82:83], 12, v[122:123]
	v_pk_fma_f32 v[124:125], v[88:89], v[108:109], v[124:125] neg_lo:[0,0,1] neg_hi:[0,0,1]
	v_pk_mul_f32 v[126:127], v[98:99], v[126:127] op_sel_hi:[0,1]
	v_pk_mul_f32 v[88:89], v[88:89], v[120:121]
	v_pk_fma_f32 v[86:87], v[94:95], v[106:107], v[86:87]
	v_lshl_add_u64 v[94:95], v[130:131], 0, v[82:83]
	v_cvt_pk_bf16_f32 v82, v126, v127
	v_pk_mul_f32 v[124:125], v[98:99], v[124:125] op_sel_hi:[0,1]
	v_pk_mul_f32 v[128:129], v[98:99], v[128:129] op_sel_hi:[0,1]
	v_pk_mul_f32 v[138:139], v[98:99], v[138:139] op_sel_hi:[0,1]
	v_pk_fma_f32 v[88:89], v[96:97], v[108:109], v[88:89]
	v_pk_mul_f32 v[86:87], v[98:99], v[86:87] op_sel_hi:[0,1]
	v_pk_mul_f32 v[90:91], v[98:99], v[84:85] op_sel_hi:[0,1]
	v_cvt_pk_bf16_f32 v83, v124, v125
	v_cvt_pk_bf16_f32 v84, v138, v139
	v_cvt_pk_bf16_f32 v85, v128, v129
	global_store_dwordx4 v[94:95], v[82:85], off
	v_pk_mul_f32 v[88:89], v[98:99], v[88:89] op_sel_hi:[0,1]
	s_nop 0
	v_cvt_pk_bf16_f32 v82, v86, v87
	v_cvt_pk_bf16_f32 v83, v88, v89
	v_cvt_pk_bf16_f32 v84, v92, v93
	v_cvt_pk_bf16_f32 v85, v90, v91
	global_store_dwordx4 v[94:95], v[82:85], off offset:256
	s_nop 1
	v_add_u32_e32 v82, 49, v166
	v_cvt_f32_ubyte0_e32 v83, v82
	v_mul_f32_e32 v84, v1, v83
	v_cmp_gt_f32_e64 s[12:13], s52, v84
	s_cbranch_vccnz .LBB0_315
	s_nop 0
	v_cndmask_b32_e64 v82, 0, v162, s[12:13]
	v_fmac_f32_e32 v82, v1, v83
	v_exp_f32_e32 v82, v82
	v_cndmask_b32_e64 v85, 0, v165, s[12:13]
	s_mov_b64 s[80:81], 0
	v_ldexp_f32 v82, v82, v85

; __device__ __forceinline__ u32x4 pack8(const f32x4& a, const f32x4& b) { u32x4 w; w.x = cvt_pk_bf16(a[0], a[1]); w.y = cvt_pk_bf16(a[2], a[3]); w.z = cvt_pk_bf16(b[0], b[1]); w.w = cvt_pk_bf16(b[2], b[3]); return w; }
;     __device__ __forceinline__ void operator()(const f32x4 (&acc)[2][2][4][2], const Unit& u, int wr, int wc, int fr, int fq) const {
;     ...
;                 for (int m = 0; m < 4; ++m) { const int row = row0 + ai * HALF + m * 16;
;                     const float tcp = (float)((row & 63) + 1);
;                     const float sc = isk ? 0.0625f * exp2f(-tcp * l2g) : exp2f(tcp * l2g);
;                     const f32x4 c0 = *(const f32x4*)(cosT + (size_t)row * 128 + cl), c1 = *(const f32x4*)(cosT + (size_t)row * 128 + cl + 4);
;                     const f32x4 s0 = *(const f32x4*)(sinT + (size_t)row * 128 + cl), s1 = *(const f32x4*)(sinT + (size_t)row * 128 + cl + 4);
;                     const f32x4 a0 = acc[ai][0][m][0], a1 = acc[ai][0][m][1], b0 = acc[ai][1][m][0], b1 = acc[ai][1][m][1];
;                     const f32x4 o10 = (a0 * c0 - b0 * s0) * sc, o11 = (a1 * c1 - b1 * s1) * sc, o20 = (b0 * c0 + a0 * s0) * sc, o21 = (b1 * c1 + a1 * s1) * sc;
;                     bf16_t* rowp = base + (size_t)row * 2048 + head * 256 + cl;
;                     *(u32x4*)rowp = pack8(o10, o11); *(u32x4*)(rowp + HALF) = pack8(o20, o21); }
.LBB0_317:
	v_or_b32_e32 v106, 48, v150
	v_ashrrev_i32_e32 v107, 31, v106
	v_lshlrev_b64 v[94:95], 9, v[106:107]
	v_lshl_add_u64 v[86:87], s[16:17], 0, v[94:95]
	v_lshl_add_u64 v[90:91], v[86:87], 0, v[132:133]
	v_lshl_add_u64 v[94:95], s[14:15], 0, v[94:95]
	v_lshl_add_u64 v[102:103], v[94:95], 0, v[132:133]
	v_lshlrev_b64 v[106:107], 12, v[106:107]
	v_lshl_add_u64 v[106:107], v[130:131], 0, v[106:107]
	s_and_b64 vcc, exec, s[10:11]
	s_mov_b64 s[12:13], -1
	s_waitcnt vmcnt(18)
	v_mov_b64_e32 v[86:87], v[242:243]
	v_mov_b64_e32 v[88:89], v[244:245]
	v_mov_b64_e32 v[90:91], v[246:247]
	v_mov_b64_e32 v[92:93], v[248:249]
	v_mov_b64_e32 v[94:95], v[234:235]
	v_mov_b64_e32 v[96:97], v[236:237]
	v_mov_b64_e32 v[102:103], v[238:239]
	v_mov_b64_e32 v[104:105], v[240:241]
	v_add_u32_e32 v251, 0x16000, v250
	global_load_dwordx4 v[238:241], v251, s[14:15] offset:16
	global_load_dwordx4 v[234:237], v251, s[14:15]
	global_load_dwordx4 v[246:249], v251, s[16:17] offset:16
	global_load_dwordx4 v[242:245], v251, s[16:17]
	v_pk_mul_f32 v[110:111], v[74:75], v[86:87]
	v_pk_mul_f32 v[108:109], v[76:77], v[88:89]
	v_pk_mul_f32 v[86:87], v[66:67], v[86:87]
	v_pk_fma_f32 v[66:67], v[66:67], v[94:95], v[110:111] neg_lo:[0,0,1] neg_hi:[0,0,1]
	v_pk_mul_f32 v[112:113], v[80:81], v[92:93]
	v_pk_mul_f32 v[118:119], v[78:79], v[90:91]
	v_pk_mul_f32 v[88:89], v[68:69], v[88:89]
	v_pk_fma_f32 v[68:69], v[68:69], v[96:97], v[108:109] neg_lo:[0,0,1] neg_hi:[0,0,1]
	v_pk_mul_f32 v[66:67], v[82:83], v[66:67] op_sel_hi:[0,1]
	v_pk_mul_f32 v[92:93], v[72:73], v[92:93]
	v_pk_mul_f32 v[90:91], v[70:71], v[90:91]
	v_pk_fma_f32 v[72:73], v[72:73], v[104:105], v[112:113] neg_lo:[0,0,1] neg_hi:[0,0,1]
	v_pk_fma_f32 v[70:71], v[70:71], v[102:103], v[118:119] neg_lo:[0,0,1] neg_hi:[0,0,1]
	v_pk_fma_f32 v[74:75], v[74:75], v[94:95], v[86:87]
	v_pk_mul_f32 v[68:69], v[82:83], v[68:69] op_sel_hi:[0,1]
	v_cvt_pk_bf16_f32 v66, v66, v67
	v_pk_fma_f32 v[76:77], v[76:77], v[96:97], v[88:89]
	v_pk_fma_f32 v[80:81], v[80:81], v[104:105], v[92:93]
	v_pk_fma_f32 v[78:79], v[78:79], v[102:103], v[90:91]
	v_pk_mul_f32 v[72:73], v[82:83], v[72:73] op_sel_hi:[0,1]
	v_pk_mul_f32 v[70:71], v[82:83], v[70:71] op_sel_hi:[0,1]
	v_pk_mul_f32 v[74:75], v[82:83], v[74:75] op_sel_hi:[0,1]
	v_cvt_pk_bf16_f32 v67, v68, v69
	v_cvt_pk_bf16_f32 v68, v70, v71
	v_cvt_pk_bf16_f32 v69, v72, v73
	global_store_dwordx4 v[106:107], v[66:69], off
	v_pk_mul_f32 v[76:77], v[82:83], v[76:77] op_sel_hi:[0,1]
	v_pk_mul_f32 v[80:81], v[82:83], v[80:81] op_sel_hi:[0,1]
	v_cvt_pk_bf16_f32 v66, v74, v75
	v_pk_mul_f32 v[78:79], v[82:83], v[78:79] op_sel_hi:[0,1]
	v_cvt_pk_bf16_f32 v67, v76, v77
	v_cvt_pk_bf16_f32 v68, v78, v79
	v_cvt_pk_bf16_f32 v69, v80, v81
	global_store_dwordx4 v[106:107], v[66:69], off offset:256
	s_cbranch_vccnz .LBB0_319
	v_cmp_gt_f32_e32 vcc, s52, v136
	s_mov_b64 s[12:13], 0
	s_nop 0
	v_cndmask_b32_e32 v67, 0, v162, vcc
	v_fmac_f32_e32 v67, v1, v135
	v_exp_f32_e32 v67, v67
	v_cndmask_b32_e32 v66, 0, v165, vcc
	v_ldexp_f32 v66, v67, v66

; __device__ __forceinline__ u32x4 pack8(const f32x4& a, const f32x4& b) { u32x4 w; w.x = cvt_pk_bf16(a[0], a[1]); w.y = cvt_pk_bf16(a[2], a[3]); w.z = cvt_pk_bf16(b[0], b[1]); w.w = cvt_pk_bf16(b[2], b[3]); return w; }
;     __device__ __forceinline__ void operator()(const f32x4 (&acc)[2][2][4][2], const Unit& u, int wr, int wc, int fr, int fq) const {
;     ...
;                 for (int m = 0; m < 4; ++m) { const int row = row0 + ai * HALF + m * 16;
;                     const float tcp = (float)((row & 63) + 1);
;                     const float sc = isk ? 0.0625f * exp2f(-tcp * l2g) : exp2f(tcp * l2g);
;                     const f32x4 c0 = *(const f32x4*)(cosT + (size_t)row * 128 + cl), c1 = *(const f32x4*)(cosT + (size_t)row * 128 + cl + 4);
;                     const f32x4 s0 = *(const f32x4*)(sinT + (size_t)row * 128 + cl), s1 = *(const f32x4*)(sinT + (size_t)row * 128 + cl + 4);
;                     const f32x4 a0 = acc[ai][0][m][0], a1 = acc[ai][0][m][1], b0 = acc[ai][1][m][0], b1 = acc[ai][1][m][1];
;                     const f32x4 o10 = (a0 * c0 - b0 * s0) * sc, o11 = (a1 * c1 - b1 * s1) * sc, o20 = (b0 * c0 + a0 * s0) * sc, o21 = (b1 * c1 + a1 * s1) * sc;
;                     bf16_t* rowp = base + (size_t)row * 2048 + head * 256 + cl;
;                     *(u32x4*)rowp = pack8(o10, o11); *(u32x4*)(rowp + HALF) = pack8(o20, o21); }
.LBB0_321:
	v_add_u32_e32 v80, 0x80, v150
	v_ashrrev_i32_e32 v81, 31, v80
	v_lshlrev_b64 v[76:77], 9, v[80:81]
	v_lshl_add_u64 v[68:69], s[16:17], 0, v[76:77]
	v_lshl_add_u64 v[72:73], v[68:69], 0, v[132:133]
	v_lshl_add_u64 v[76:77], s[14:15], 0, v[76:77]
	v_lshl_add_u64 v[86:87], v[76:77], 0, v[132:133]
	v_lshlrev_b64 v[80:81], 12, v[80:81]
	v_lshl_add_u64 v[80:81], v[130:131], 0, v[80:81]
	s_and_b64 vcc, exec, s[10:11]
	s_mov_b64 s[12:13], -1
	s_waitcnt vmcnt(20)
	v_mov_b64_e32 v[68:69], v[194:195]
	v_mov_b64_e32 v[70:71], v[196:197]
	v_mov_b64_e32 v[72:73], v[198:199]
	v_mov_b64_e32 v[74:75], v[200:201]
	v_mov_b64_e32 v[76:77], v[186:187]
	v_mov_b64_e32 v[78:79], v[188:189]
	v_mov_b64_e32 v[86:87], v[190:191]
	v_mov_b64_e32 v[88:89], v[192:193]
	v_pk_mul_f32 v[92:93], v[58:59], v[68:69]
	v_pk_mul_f32 v[90:91], v[60:61], v[70:71]
	v_pk_mul_f32 v[68:69], v[50:51], v[68:69]
	v_pk_fma_f32 v[50:51], v[50:51], v[76:77], v[92:93] neg_lo:[0,0,1] neg_hi:[0,0,1]
	v_pk_mul_f32 v[94:95], v[64:65], v[74:75]
	v_pk_mul_f32 v[96:97], v[62:63], v[72:73]
	v_pk_mul_f32 v[70:71], v[52:53], v[70:71]
	v_pk_fma_f32 v[52:53], v[52:53], v[78:79], v[90:91] neg_lo:[0,0,1] neg_hi:[0,0,1]
	v_pk_mul_f32 v[50:51], v[66:67], v[50:51] op_sel_hi:[0,1]
	v_pk_mul_f32 v[74:75], v[56:57], v[74:75]
	v_pk_mul_f32 v[72:73], v[54:55], v[72:73]
	v_pk_fma_f32 v[56:57], v[56:57], v[88:89], v[94:95] neg_lo:[0,0,1] neg_hi:[0,0,1]
	v_pk_fma_f32 v[54:55], v[54:55], v[86:87], v[96:97] neg_lo:[0,0,1] neg_hi:[0,0,1]
	v_pk_fma_f32 v[58:59], v[58:59], v[76:77], v[68:69]
	v_pk_mul_f32 v[52:53], v[66:67], v[52:53] op_sel_hi:[0,1]
	v_cvt_pk_bf16_f32 v50, v50, v51
	v_pk_fma_f32 v[60:61], v[60:61], v[78:79], v[70:71]
	v_pk_fma_f32 v[64:65], v[64:65], v[88:89], v[74:75]
	v_pk_fma_f32 v[62:63], v[62:63], v[86:87], v[72:73]
	v_pk_mul_f32 v[56:57], v[66:67], v[56:57] op_sel_hi:[0,1]
	v_pk_mul_f32 v[54:55], v[66:67], v[54:55] op_sel_hi:[0,1]
	v_pk_mul_f32 v[58:59], v[66:67], v[58:59] op_sel_hi:[0,1]
	v_cvt_pk_bf16_f32 v51, v52, v53
	v_cvt_pk_bf16_f32 v52, v54, v55
	v_cvt_pk_bf16_f32 v53, v56, v57
	global_store_dwordx4 v[80:81], v[50:53], off
	v_pk_mul_f32 v[60:61], v[66:67], v[60:61] op_sel_hi:[0,1]
	v_pk_mul_f32 v[64:65], v[66:67], v[64:65] op_sel_hi:[0,1]
	v_cvt_pk_bf16_f32 v50, v58, v59
	v_pk_mul_f32 v[62:63], v[66:67], v[62:63] op_sel_hi:[0,1]
	v_cvt_pk_bf16_f32 v51, v60, v61
	v_cvt_pk_bf16_f32 v52, v62, v63
	v_cvt_pk_bf16_f32 v53, v64, v65
	global_store_dwordx4 v[80:81], v[50:53], off offset:256
	s_cbranch_vccnz .LBB0_323
	v_cmp_gt_f32_e32 vcc, s52, v116
	s_mov_b64 s[12:13], 0
	s_nop 0
	v_cndmask_b32_e32 v51, 0, v162, vcc
	v_fmac_f32_e32 v51, v1, v115
	v_exp_f32_e32 v51, v51
	v_cndmask_b32_e32 v50, 0, v165, vcc
	v_ldexp_f32 v50, v51, v50

; __device__ __forceinline__ u32x4 pack8(const f32x4& a, const f32x4& b) { u32x4 w; w.x = cvt_pk_bf16(a[0], a[1]); w.y = cvt_pk_bf16(a[2], a[3]); w.z = cvt_pk_bf16(b[0], b[1]); w.w = cvt_pk_bf16(b[2], b[3]); return w; }
;     __device__ __forceinline__ void operator()(const f32x4 (&acc)[2][2][4][2], const Unit& u, int wr, int wc, int fr, int fq) const {
;     ...
;                 for (int m = 0; m < 4; ++m) { const int row = row0 + ai * HALF + m * 16;
;                     const float tcp = (float)((row & 63) + 1);
;                     const float sc = isk ? 0.0625f * exp2f(-tcp * l2g) : exp2f(tcp * l2g);
;                     const f32x4 c0 = *(const f32x4*)(cosT + (size_t)row * 128 + cl), c1 = *(const f32x4*)(cosT + (size_t)row * 128 + cl + 4);
;                     const f32x4 s0 = *(const f32x4*)(sinT + (size_t)row * 128 + cl), s1 = *(const f32x4*)(sinT + (size_t)row * 128 + cl + 4);
;                     const f32x4 a0 = acc[ai][0][m][0], a1 = acc[ai][0][m][1], b0 = acc[ai][1][m][0], b1 = acc[ai][1][m][1];
;                     const f32x4 o10 = (a0 * c0 - b0 * s0) * sc, o11 = (a1 * c1 - b1 * s1) * sc, o20 = (b0 * c0 + a0 * s0) * sc, o21 = (b1 * c1 + a1 * s1) * sc;
;                     bf16_t* rowp = base + (size_t)row * 2048 + head * 256 + cl;
;                     *(u32x4*)rowp = pack8(o10, o11); *(u32x4*)(rowp + HALF) = pack8(o20, o21); }
.LBB0_325:
	v_add_u32_e32 v68, 0x90, v150
	v_ashrrev_i32_e32 v69, 31, v68
	v_lshlrev_b64 v[60:61], 9, v[68:69]
	v_lshl_add_u64 v[52:53], s[16:17], 0, v[60:61]
	v_lshl_add_u64 v[56:57], v[52:53], 0, v[132:133]
	v_lshl_add_u64 v[60:61], s[14:15], 0, v[60:61]
	v_lshl_add_u64 v[64:65], v[60:61], 0, v[132:133]
	v_lshlrev_b64 v[68:69], 12, v[68:69]
	v_lshl_add_u64 v[68:69], v[130:131], 0, v[68:69]
	s_and_b64 vcc, exec, s[10:11]
	s_mov_b64 s[12:13], -1
	s_waitcnt vmcnt(16)
	v_mov_b64_e32 v[52:53], v[210:211]
	v_mov_b64_e32 v[54:55], v[212:213]
	v_mov_b64_e32 v[56:57], v[214:215]
	v_mov_b64_e32 v[58:59], v[216:217]
	v_mov_b64_e32 v[60:61], v[202:203]
	v_mov_b64_e32 v[62:63], v[204:205]
	v_mov_b64_e32 v[64:65], v[206:207]
	v_mov_b64_e32 v[66:67], v[208:209]
	v_pk_mul_f32 v[72:73], v[42:43], v[52:53]
	v_pk_mul_f32 v[70:71], v[44:45], v[54:55]
	v_pk_mul_f32 v[52:53], v[34:35], v[52:53]
	v_pk_fma_f32 v[34:35], v[34:35], v[60:61], v[72:73] neg_lo:[0,0,1] neg_hi:[0,0,1]
	v_pk_mul_f32 v[74:75], v[48:49], v[58:59]
	v_pk_mul_f32 v[76:77], v[46:47], v[56:57]
	v_pk_mul_f32 v[54:55], v[36:37], v[54:55]
	v_pk_fma_f32 v[36:37], v[36:37], v[62:63], v[70:71] neg_lo:[0,0,1] neg_hi:[0,0,1]
	v_pk_mul_f32 v[34:35], v[50:51], v[34:35] op_sel_hi:[0,1]
	v_pk_mul_f32 v[58:59], v[40:41], v[58:59]
	v_pk_mul_f32 v[56:57], v[38:39], v[56:57]
	v_pk_fma_f32 v[40:41], v[40:41], v[66:67], v[74:75] neg_lo:[0,0,1] neg_hi:[0,0,1]
	v_pk_fma_f32 v[38:39], v[38:39], v[64:65], v[76:77] neg_lo:[0,0,1] neg_hi:[0,0,1]
	v_pk_fma_f32 v[42:43], v[42:43], v[60:61], v[52:53]
	v_pk_mul_f32 v[36:37], v[50:51], v[36:37] op_sel_hi:[0,1]
	v_cvt_pk_bf16_f32 v34, v34, v35
	v_pk_fma_f32 v[44:45], v[44:45], v[62:63], v[54:55]
	v_pk_fma_f32 v[48:49], v[48:49], v[66:67], v[58:59]
	v_pk_fma_f32 v[46:47], v[46:47], v[64:65], v[56:57]
	v_pk_mul_f32 v[40:41], v[50:51], v[40:41] op_sel_hi:[0,1]
	v_pk_mul_f32 v[38:39], v[50:51], v[38:39] op_sel_hi:[0,1]
	v_pk_mul_f32 v[42:43], v[50:51], v[42:43] op_sel_hi:[0,1]
	v_cvt_pk_bf16_f32 v35, v36, v37
	v_cvt_pk_bf16_f32 v36, v38, v39
	v_cvt_pk_bf16_f32 v37, v40, v41
	global_store_dwordx4 v[68:69], v[34:37], off
	v_pk_mul_f32 v[44:45], v[50:51], v[44:45] op_sel_hi:[0,1]
	v_pk_mul_f32 v[48:49], v[50:51], v[48:49] op_sel_hi:[0,1]
	v_cvt_pk_bf16_f32 v34, v42, v43
	v_pk_mul_f32 v[46:47], v[50:51], v[46:47] op_sel_hi:[0,1]
	v_cvt_pk_bf16_f32 v35, v44, v45
	v_cvt_pk_bf16_f32 v36, v46, v47
	v_cvt_pk_bf16_f32 v37, v48, v49
	global_store_dwordx4 v[68:69], v[34:37], off offset:256
	s_cbranch_vccnz .LBB0_327
	v_cmp_gt_f32_e32 vcc, s52, v100
	s_mov_b64 s[12:13], 0
	s_nop 0
	v_cndmask_b32_e32 v35, 0, v162, vcc
	v_fmac_f32_e32 v35, v1, v99
	v_exp_f32_e32 v35, v35
	v_cndmask_b32_e32 v34, 0, v165, vcc
	v_ldexp_f32 v34, v35, v34

; __device__ __forceinline__ u32x4 pack8(const f32x4& a, const f32x4& b) { u32x4 w; w.x = cvt_pk_bf16(a[0], a[1]); w.y = cvt_pk_bf16(a[2], a[3]); w.z = cvt_pk_bf16(b[0], b[1]); w.w = cvt_pk_bf16(b[2], b[3]); return w; }
;     __device__ __forceinline__ void operator()(const f32x4 (&acc)[2][2][4][2], const Unit& u, int wr, int wc, int fr, int fq) const {
;     ...
;                 for (int m = 0; m < 4; ++m) { const int row = row0 + ai * HALF + m * 16;
;                     const float tcp = (float)((row & 63) + 1);
;                     const float sc = isk ? 0.0625f * exp2f(-tcp * l2g) : exp2f(tcp * l2g);
;                     const f32x4 c0 = *(const f32x4*)(cosT + (size_t)row * 128 + cl), c1 = *(const f32x4*)(cosT + (size_t)row * 128 + cl + 4);
;                     const f32x4 s0 = *(const f32x4*)(sinT + (size_t)row * 128 + cl), s1 = *(const f32x4*)(sinT + (size_t)row * 128 + cl + 4);
;                     const f32x4 a0 = acc[ai][0][m][0], a1 = acc[ai][0][m][1], b0 = acc[ai][1][m][0], b1 = acc[ai][1][m][1];
;                     const f32x4 o10 = (a0 * c0 - b0 * s0) * sc, o11 = (a1 * c1 - b1 * s1) * sc, o20 = (b0 * c0 + a0 * s0) * sc, o21 = (b1 * c1 + a1 * s1) * sc;
;                     bf16_t* rowp = base + (size_t)row * 2048 + head * 256 + cl;
;                     *(u32x4*)rowp = pack8(o10, o11); *(u32x4*)(rowp + HALF) = pack8(o20, o21); }
.LBB0_329:
	v_add_u32_e32 v52, 0xa0, v150
	v_ashrrev_i32_e32 v53, 31, v52
	v_lshlrev_b64 v[44:45], 9, v[52:53]
	v_lshl_add_u64 v[36:37], s[16:17], 0, v[44:45]
	v_lshl_add_u64 v[40:41], v[36:37], 0, v[132:133]
	v_lshl_add_u64 v[44:45], s[14:15], 0, v[44:45]
	v_lshl_add_u64 v[48:49], v[44:45], 0, v[132:133]
	v_lshlrev_b64 v[52:53], 12, v[52:53]
	v_lshl_add_u64 v[52:53], v[130:131], 0, v[52:53]
	s_and_b64 vcc, exec, s[10:11]
	s_mov_b64 s[10:11], -1
	s_waitcnt vmcnt(12)
	v_mov_b64_e32 v[36:37], v[226:227]
	v_mov_b64_e32 v[38:39], v[228:229]
	v_mov_b64_e32 v[40:41], v[230:231]
	v_mov_b64_e32 v[42:43], v[232:233]
	v_mov_b64_e32 v[44:45], v[218:219]
	v_mov_b64_e32 v[46:47], v[220:221]
	v_mov_b64_e32 v[48:49], v[222:223]
	v_mov_b64_e32 v[50:51], v[224:225]
	v_pk_mul_f32 v[56:57], v[26:27], v[36:37]
	v_pk_mul_f32 v[54:55], v[28:29], v[38:39]
	v_pk_mul_f32 v[36:37], v[18:19], v[36:37]
	v_pk_fma_f32 v[18:19], v[18:19], v[44:45], v[56:57] neg_lo:[0,0,1] neg_hi:[0,0,1]
	v_pk_mul_f32 v[58:59], v[32:33], v[42:43]
	v_pk_mul_f32 v[60:61], v[30:31], v[40:41]
	v_pk_mul_f32 v[38:39], v[20:21], v[38:39]
	v_pk_fma_f32 v[20:21], v[20:21], v[46:47], v[54:55] neg_lo:[0,0,1] neg_hi:[0,0,1]
	v_pk_mul_f32 v[18:19], v[34:35], v[18:19] op_sel_hi:[0,1]
	v_pk_mul_f32 v[42:43], v[24:25], v[42:43]
	v_pk_mul_f32 v[40:41], v[22:23], v[40:41]
	v_pk_fma_f32 v[24:25], v[24:25], v[50:51], v[58:59] neg_lo:[0,0,1] neg_hi:[0,0,1]
	v_pk_fma_f32 v[22:23], v[22:23], v[48:49], v[60:61] neg_lo:[0,0,1] neg_hi:[0,0,1]
	v_pk_fma_f32 v[26:27], v[26:27], v[44:45], v[36:37]
	v_pk_mul_f32 v[20:21], v[34:35], v[20:21] op_sel_hi:[0,1]
	v_cvt_pk_bf16_f32 v18, v18, v19
	v_pk_fma_f32 v[28:29], v[28:29], v[46:47], v[38:39]
	v_pk_fma_f32 v[32:33], v[32:33], v[50:51], v[42:43]
	v_pk_fma_f32 v[30:31], v[30:31], v[48:49], v[40:41]
	v_pk_mul_f32 v[24:25], v[34:35], v[24:25] op_sel_hi:[0,1]
	v_pk_mul_f32 v[22:23], v[34:35], v[22:23] op_sel_hi:[0,1]
	v_pk_mul_f32 v[26:27], v[34:35], v[26:27] op_sel_hi:[0,1]
	v_cvt_pk_bf16_f32 v19, v20, v21
	v_cvt_pk_bf16_f32 v20, v22, v23
	v_cvt_pk_bf16_f32 v21, v24, v25
	global_store_dwordx4 v[52:53], v[18:21], off
	v_pk_mul_f32 v[28:29], v[34:35], v[28:29] op_sel_hi:[0,1]
	v_pk_mul_f32 v[32:33], v[34:35], v[32:33] op_sel_hi:[0,1]
	v_cvt_pk_bf16_f32 v18, v26, v27
	v_pk_mul_f32 v[30:31], v[34:35], v[30:31] op_sel_hi:[0,1]
	v_cvt_pk_bf16_f32 v19, v28, v29
	v_cvt_pk_bf16_f32 v20, v30, v31
	v_cvt_pk_bf16_f32 v21, v32, v33
	global_store_dwordx4 v[52:53], v[18:21], off offset:256
	s_cbranch_vccnz .LBB0_331
	v_cmp_gt_f32_e32 vcc, s52, v84
	s_mov_b64 s[10:11], 0
	s_nop 0
	v_cndmask_b32_e32 v19, 0, v162, vcc
	v_fmac_f32_e32 v19, v1, v83
	v_exp_f32_e32 v19, v19
	v_cndmask_b32_e32 v18, 0, v165, vcc
	v_ldexp_f32 v18, v19, v18

; __device__ __forceinline__ u32x4 pack8(const f32x4& a, const f32x4& b) { u32x4 w; w.x = cvt_pk_bf16(a[0], a[1]); w.y = cvt_pk_bf16(a[2], a[3]); w.z = cvt_pk_bf16(b[0], b[1]); w.w = cvt_pk_bf16(b[2], b[3]); return w; }
;     __device__ __forceinline__ void operator()(const f32x4 (&acc)[2][2][4][2], const Unit& u, int wr, int wc, int fr, int fq) const {
;     ...
;                 for (int m = 0; m < 4; ++m) { const int row = row0 + ai * HALF + m * 16;
;                     const float tcp = (float)((row & 63) + 1);
;                     const float sc = isk ? 0.0625f * exp2f(-tcp * l2g) : exp2f(tcp * l2g);
;                     const f32x4 c0 = *(const f32x4*)(cosT + (size_t)row * 128 + cl), c1 = *(const f32x4*)(cosT + (size_t)row * 128 + cl + 4);
;                     const f32x4 s0 = *(const f32x4*)(sinT + (size_t)row * 128 + cl), s1 = *(const f32x4*)(sinT + (size_t)row * 128 + cl + 4);
;                     const f32x4 a0 = acc[ai][0][m][0], a1 = acc[ai][0][m][1], b0 = acc[ai][1][m][0], b1 = acc[ai][1][m][1];
;                     const f32x4 o10 = (a0 * c0 - b0 * s0) * sc, o11 = (a1 * c1 - b1 * s1) * sc, o20 = (b0 * c0 + a0 * s0) * sc, o21 = (b1 * c1 + a1 * s1) * sc;
;                     bf16_t* rowp = base + (size_t)row * 2048 + head * 256 + cl;
;                     *(u32x4*)rowp = pack8(o10, o11); *(u32x4*)(rowp + HALF) = pack8(o20, o21); }
.LBB0_333:
	v_add_u32_e32 v36, 0xb0, v150
	v_ashrrev_i32_e32 v37, 31, v36
	v_lshlrev_b64 v[28:29], 9, v[36:37]
	v_lshl_add_u64 v[20:21], s[16:17], 0, v[28:29]
	v_lshl_add_u64 v[24:25], v[20:21], 0, v[132:133]
	v_lshl_add_u64 v[28:29], s[14:15], 0, v[28:29]
	v_lshl_add_u64 v[32:33], v[28:29], 0, v[132:133]
	v_lshlrev_b64 v[36:37], 12, v[36:37]
	v_lshl_add_u64 v[154:155], v[130:131], 0, v[36:37]
	s_waitcnt vmcnt(8)
	v_mov_b64_e32 v[20:21], v[242:243]
	v_mov_b64_e32 v[22:23], v[244:245]
	v_mov_b64_e32 v[24:25], v[246:247]
	v_mov_b64_e32 v[26:27], v[248:249]
	v_mov_b64_e32 v[28:29], v[234:235]
	v_mov_b64_e32 v[30:31], v[236:237]
	v_mov_b64_e32 v[32:33], v[238:239]
	v_mov_b64_e32 v[34:35], v[240:241]
	v_pk_mul_f32 v[36:37], v[12:13], v[22:23]
	v_pk_mul_f32 v[38:39], v[10:11], v[20:21]
	v_pk_mul_f32 v[40:41], v[16:17], v[26:27]
	v_pk_mul_f32 v[42:43], v[14:15], v[24:25]
	v_pk_mul_f32 v[22:23], v[4:5], v[22:23]
	v_pk_mul_f32 v[20:21], v[2:3], v[20:21]
	v_pk_mul_f32 v[26:27], v[8:9], v[26:27]
	v_pk_mul_f32 v[24:25], v[6:7], v[24:25]
	v_pk_fma_f32 v[4:5], v[4:5], v[30:31], v[36:37] neg_lo:[0,0,1] neg_hi:[0,0,1]
	v_pk_fma_f32 v[2:3], v[2:3], v[28:29], v[38:39] neg_lo:[0,0,1] neg_hi:[0,0,1]
	v_pk_fma_f32 v[8:9], v[8:9], v[34:35], v[40:41] neg_lo:[0,0,1] neg_hi:[0,0,1]
	v_pk_fma_f32 v[6:7], v[6:7], v[32:33], v[42:43] neg_lo:[0,0,1] neg_hi:[0,0,1]
	v_pk_fma_f32 v[12:13], v[12:13], v[30:31], v[22:23]
	v_pk_fma_f32 v[10:11], v[10:11], v[28:29], v[20:21]
	v_pk_fma_f32 v[16:17], v[16:17], v[34:35], v[26:27]
	v_pk_fma_f32 v[14:15], v[14:15], v[32:33], v[24:25]
	v_pk_mul_f32 v[4:5], v[18:19], v[4:5] op_sel_hi:[0,1]
	v_pk_mul_f32 v[2:3], v[18:19], v[2:3] op_sel_hi:[0,1]
	v_pk_mul_f32 v[8:9], v[18:19], v[8:9] op_sel_hi:[0,1]
	v_pk_mul_f32 v[6:7], v[18:19], v[6:7] op_sel_hi:[0,1]
	v_pk_mul_f32 v[12:13], v[18:19], v[12:13] op_sel_hi:[0,1]
	v_pk_mul_f32 v[10:11], v[18:19], v[10:11] op_sel_hi:[0,1]
	v_pk_mul_f32 v[16:17], v[18:19], v[16:17] op_sel_hi:[0,1]
	v_pk_mul_f32 v[14:15], v[18:19], v[14:15] op_sel_hi:[0,1]
	v_cvt_pk_bf16_f32 v2, v2, v3
	v_cvt_pk_bf16_f32 v3, v4, v5
	v_cvt_pk_bf16_f32 v4, v6, v7
	v_cvt_pk_bf16_f32 v5, v8, v9
	global_store_dwordx4 v[154:155], v[2:5], off
	v_cvt_pk_bf16_f32 v130, v10, v11
	v_cvt_pk_bf16_f32 v131, v12, v13
	v_cvt_pk_bf16_f32 v132, v14, v15
	v_cvt_pk_bf16_f32 v133, v16, v17
	s_andn2_b64 vcc, exec, s[8:9]
	s_mov_b64 s[8:9], -1
	global_store_dwordx4 v[154:155], v[130:133], off offset:256
	s_cbranch_vccnz .LBB0_258
